# v12: v08 + gq/gk max loads batched in mixer prologue + ctx_fixup loads batched (37 loads per row under one wait)
# speedup vs baseline: 1.0180x; 1.0010x over previous
.LBB0_271:
	s_mov_b64 s[98:99], 0x800000
	v_mov_b64_e32 v[18:19], v[16:17]
	global_load_dwordx4 v[20:23], v[18:19], off
	global_load_dwordx4 v[24:27], v[18:19], off offset:1024
	global_load_dwordx4 v[28:31], v[18:19], off offset:2048
	global_load_dwordx4 v[32:35], v[18:19], off offset:3072
	v_lshl_add_u64 v[18:19], v[18:19], 0, s[98:99]
	global_load_dwordx4 v[36:39], v[18:19], off
	global_load_dwordx4 v[40:43], v[18:19], off offset:1024
	global_load_dwordx4 v[44:47], v[18:19], off offset:2048
	global_load_dwordx4 v[48:51], v[18:19], off offset:3072
	v_lshl_add_u64 v[18:19], v[18:19], 0, s[98:99]
	global_load_dwordx4 v[52:55], v[18:19], off
	global_load_dwordx4 v[56:59], v[18:19], off offset:1024
	global_load_dwordx4 v[60:63], v[18:19], off offset:2048
	global_load_dwordx4 v[64:67], v[18:19], off offset:3072
	v_lshl_add_u64 v[18:19], v[18:19], 0, s[98:99]
	global_load_dwordx4 v[68:71], v[18:19], off
	global_load_dwordx4 v[72:75], v[18:19], off offset:1024
	global_load_dwordx4 v[76:79], v[18:19], off offset:2048
	global_load_dwordx4 v[80:83], v[18:19], off offset:3072
	v_lshl_add_u64 v[18:19], v[18:19], 0, s[98:99]
	global_load_dwordx4 v[84:87], v[18:19], off
	global_load_dwordx4 v[88:91], v[18:19], off offset:1024
	global_load_dwordx4 v[92:95], v[18:19], off offset:2048
	global_load_dwordx4 v[96:99], v[18:19], off offset:3072
	v_lshl_add_u64 v[18:19], v[18:19], 0, s[98:99]
	global_load_dwordx4 v[100:103], v[18:19], off
	global_load_dwordx4 v[104:107], v[18:19], off offset:1024
	global_load_dwordx4 v[108:111], v[18:19], off offset:2048
	global_load_dwordx4 v[114:117], v[18:19], off offset:3072
	v_lshl_add_u64 v[18:19], v[18:19], 0, s[98:99]
	global_load_dwordx4 v[118:121], v[18:19], off
	global_load_dwordx4 v[122:125], v[18:19], off offset:1024
	global_load_dwordx4 v[126:129], v[18:19], off offset:2048
	global_load_dwordx4 v[130:133], v[18:19], off offset:3072
	v_lshl_add_u64 v[18:19], v[18:19], 0, s[98:99]
	global_load_dwordx4 v[134:137], v[18:19], off
	global_load_dwordx4 v[138:141], v[18:19], off offset:1024
	global_load_dwordx4 v[142:145], v[18:19], off offset:2048
	global_load_dwordx4 v[146:149], v[18:19], off offset:3072
	v_add_co_u32_e32 v18, vcc, 0xea200000, v16
	s_nop 1
	v_addc_co_u32_e32 v19, vcc, -1, v17, vcc
	global_load_dwordx4 v[150:153], v[18:19], off
	global_load_dwordx4 v[154:157], v[18:19], off offset:1024
	global_load_dwordx4 v[158:161], v[18:19], off offset:2048
	global_load_dwordx4 v[162:165], v[18:19], off offset:3072
	global_load_dwordx4 v[166:169], v[14:15], off
	v_add_u32_e32 v12, s30, v12
	s_waitcnt vmcnt(0) lgkmcnt(0)
	v_pk_add_f32 v[20:21], v[20:21], v[36:37]
	v_pk_add_f32 v[22:23], v[22:23], v[38:39]
	v_pk_add_f32 v[20:21], v[20:21], v[52:53]
	v_pk_add_f32 v[22:23], v[22:23], v[54:55]
	v_pk_add_f32 v[20:21], v[20:21], v[68:69]
	v_pk_add_f32 v[22:23], v[22:23], v[70:71]
	v_pk_add_f32 v[20:21], v[20:21], v[84:85]
	v_pk_add_f32 v[22:23], v[22:23], v[86:87]
	v_pk_add_f32 v[20:21], v[20:21], v[100:101]
	v_pk_add_f32 v[22:23], v[22:23], v[102:103]
	v_pk_add_f32 v[20:21], v[20:21], v[118:119]
	v_pk_add_f32 v[22:23], v[22:23], v[120:121]
	v_pk_add_f32 v[20:21], v[20:21], v[134:135]
	v_pk_add_f32 v[22:23], v[22:23], v[136:137]
	v_pk_fma_f32 v[150:151], v[20:21], v[0:1], v[150:151]
	v_pk_fma_f32 v[152:153], v[22:23], v[2:3], v[152:153]
	global_store_dwordx4 v[18:19], v[150:153], off
	v_pk_add_f32 v[24:25], v[24:25], v[40:41]
	v_pk_add_f32 v[26:27], v[26:27], v[42:43]
	v_pk_add_f32 v[24:25], v[24:25], v[56:57]
	v_pk_add_f32 v[26:27], v[26:27], v[58:59]
	v_pk_add_f32 v[24:25], v[24:25], v[72:73]
	v_pk_add_f32 v[26:27], v[26:27], v[74:75]
	v_pk_add_f32 v[24:25], v[24:25], v[88:89]
	v_pk_add_f32 v[26:27], v[26:27], v[90:91]
	v_pk_add_f32 v[24:25], v[24:25], v[104:105]
	v_pk_add_f32 v[26:27], v[26:27], v[106:107]
	v_pk_add_f32 v[24:25], v[24:25], v[122:123]
	v_pk_add_f32 v[26:27], v[26:27], v[124:125]
	v_pk_add_f32 v[24:25], v[24:25], v[138:139]
	v_pk_add_f32 v[26:27], v[26:27], v[140:141]
	v_pk_fma_f32 v[154:155], v[24:25], v[4:5], v[154:155]
	v_pk_fma_f32 v[156:157], v[26:27], v[6:7], v[156:157]
	global_store_dwordx4 v[18:19], v[154:157], off offset:1024
	v_pk_add_f32 v[28:29], v[28:29], v[44:45]
	v_pk_add_f32 v[30:31], v[30:31], v[46:47]
	v_pk_add_f32 v[28:29], v[28:29], v[60:61]
	v_pk_add_f32 v[30:31], v[30:31], v[62:63]
	v_pk_add_f32 v[28:29], v[28:29], v[76:77]
	v_pk_add_f32 v[30:31], v[30:31], v[78:79]
	v_pk_add_f32 v[28:29], v[28:29], v[92:93]
	v_pk_add_f32 v[30:31], v[30:31], v[94:95]
	v_pk_add_f32 v[28:29], v[28:29], v[108:109]
	v_pk_add_f32 v[30:31], v[30:31], v[110:111]
	v_pk_add_f32 v[28:29], v[28:29], v[126:127]
	v_pk_add_f32 v[30:31], v[30:31], v[128:129]
	v_pk_add_f32 v[28:29], v[28:29], v[142:143]
	v_pk_add_f32 v[30:31], v[30:31], v[144:145]
	v_pk_fma_f32 v[158:159], v[28:29], v[8:9], v[158:159]
	v_pk_fma_f32 v[160:161], v[30:31], v[10:11], v[160:161]
	global_store_dwordx4 v[18:19], v[158:161], off offset:2048
	v_pk_add_f32 v[32:33], v[32:33], v[48:49]
	v_pk_add_f32 v[34:35], v[34:35], v[50:51]
	v_pk_add_f32 v[32:33], v[32:33], v[64:65]
	v_pk_add_f32 v[34:35], v[34:35], v[66:67]
	v_pk_add_f32 v[32:33], v[32:33], v[80:81]
	v_pk_add_f32 v[34:35], v[34:35], v[82:83]
	v_pk_add_f32 v[32:33], v[32:33], v[96:97]
	v_pk_add_f32 v[34:35], v[34:35], v[98:99]
	v_pk_add_f32 v[32:33], v[32:33], v[114:115]
	v_pk_add_f32 v[34:35], v[34:35], v[116:117]
	v_pk_add_f32 v[32:33], v[32:33], v[130:131]
	v_pk_add_f32 v[34:35], v[34:35], v[132:133]
	v_pk_add_f32 v[32:33], v[32:33], v[146:147]
	v_pk_add_f32 v[34:35], v[34:35], v[148:149]
	v_pk_fma_f32 v[162:163], v[32:33], v[166:167], v[162:163]
	v_pk_fma_f32 v[164:165], v[34:35], v[168:169], v[164:165]
	global_store_dwordx4 v[18:19], v[162:165], off offset:3072
	s_movk_i32 s10, 0x7ff
	v_cmp_lt_i32_e32 vcc, s10, v12
	v_lshl_add_u64 v[16:17], v[16:17], 0, s[42:43]
	s_or_b64 s[8:9], vcc, s[8:9]
	s_andn2_b64 exec, exec, s[8:9]
	s_cbranch_execnz .LBB0_271

.LBB0_998:
	s_or_b64 exec, exec, s[2:3]
	s_waitcnt lgkmcnt(0)
	v_mov_b32_e32 v0, v246
	v_readlane_b32 s7, v255, 18
	s_barrier
	s_getreg_b32 s39, hwreg(HW_REG_XCC_ID, 0, 4)
	s_add_u32 s2, s50, s7
	v_and_b32_e32 v2, 63, v0
	v_readlane_b32 s6, v255, 17
	s_addc_u32 s3, s51, s6
	v_lshlrev_b32_e32 v0, 2, v2
	v_mov_b32_e32 v1, v113
	v_lshl_add_u64 v[4:5], s[2:3], 0, v[0:1]
	s_add_u32 s2, s48, s7
	s_addc_u32 s3, s49, s6
	v_lshl_add_u64 v[6:7], s[2:3], 0, v[0:1]
	v_or_b32_e32 v3, 0xffffffc0, v2
	v_mov_b32_e32 v8, 0
	s_mov_b64 s[2:3], 0
	v_mov_b32_e32 v1, 0
	s_mov_b64 s[6:7], 0x100
	global_load_dword v9, v[6:7], off
	global_load_dword v10, v[4:5], off
	v_mov_b32_e32 v11, 0
	v_mov_b32_e32 v12, 0
	v_cmp_gt_u32_e32 vcc, 32, v2
	s_and_saveexec_b64 s[2:3], vcc
	global_load_dword v11, v[6:7], off offset:256
	global_load_dword v12, v[4:5], off offset:256
	s_or_b64 exec, exec, s[2:3]
	s_waitcnt vmcnt(0)
	v_max_f32_e64 v9, |v9|, |v9|
	v_max_f32_e32 v8, v8, v9
	v_max_f32_e64 v11, |v11|, |v11|
	v_max_f32_e32 v8, v8, v11
	v_max_f32_e64 v10, |v10|, |v10|
	v_max_f32_e32 v1, v1, v10
	v_max_f32_e64 v12, |v12|, |v12|
	v_max_f32_e32 v1, v1, v12
	s_or_b64 exec, exec, s[2:3]
	s_load_dwordx4 s[44:47], s[84:85], 0xa0
	s_load_dwordx2 s[10:11], s[84:85], 0xb0
	v_readlane_b32 s2, v254, 62
	v_sub_u32_e32 v3, 0xe87, v2
	v_lshrrev_b32_e32 v3, 6, v3
	v_or_b32_e32 v112, s2, v2
	v_lshlrev_b64 v[4:5], 2, v[112:113]
	s_waitcnt lgkmcnt(0)
	v_lshl_add_u64 v[6:7], s[44:45], 0, v[4:5]
	v_lshl_add_u64 v[4:5], s[46:47], 0, v[4:5]
	global_load_dword v7, v[6:7], off
	v_add_u32_e32 v10, 1, v3
	global_load_dword v6, v[4:5], off
	v_or_b32_e32 v3, 64, v2
	v_readlane_b32 s3, v254, 63
	s_mov_b32 s12, 2
	v_and_b32_e32 v9, 62, v10
	v_mov_b32_e32 v12, 0
	s_mov_b64 s[8:9], 0
	v_mov_b64_e32 v[4:5], v[2:3]
	v_mov_b32_e32 v3, 0
	v_readlane_b32 s13, v255, 10
	v_readlane_b32 s14, v255, 11
	s_nop 1
	v_add_u32_e32 v112, s13, v2
	v_lshl_add_u64 v[12:13], v[112:113], 2, s[10:11]
	s_mov_b64 s[98:99], 0x1000
	v_mov_b32_e32 v4, 0
	global_load_dword v16, v[12:13], off
	global_load_dword v17, v[12:13], off offset:256
	global_load_dword v18, v[12:13], off offset:512
	global_load_dword v19, v[12:13], off offset:768
	global_load_dword v20, v[12:13], off offset:1024
	global_load_dword v21, v[12:13], off offset:1280
	global_load_dword v22, v[12:13], off offset:1536
	global_load_dword v23, v[12:13], off offset:1792
	global_load_dword v24, v[12:13], off offset:2048
	global_load_dword v25, v[12:13], off offset:2304
	global_load_dword v26, v[12:13], off offset:2560
	global_load_dword v27, v[12:13], off offset:2816
	global_load_dword v28, v[12:13], off offset:3072
	global_load_dword v29, v[12:13], off offset:3328
	global_load_dword v30, v[12:13], off offset:3584
	global_load_dword v31, v[12:13], off offset:3840
	v_lshl_add_u64 v[12:13], v[12:13], 0, s[98:99]
	s_waitcnt vmcnt(0)
	v_max_f32_e64 v16, |v16|, |v16|
	v_max_f32_e32 v4, v4, v16
	v_max_f32_e64 v17, |v17|, |v17|
	v_max_f32_e32 v4, v4, v17
	v_max_f32_e64 v18, |v18|, |v18|
	v_max_f32_e32 v4, v4, v18
	v_max_f32_e64 v19, |v19|, |v19|
	v_max_f32_e32 v4, v4, v19
	v_max_f32_e64 v20, |v20|, |v20|
	v_max_f32_e32 v4, v4, v20
	v_max_f32_e64 v21, |v21|, |v21|
	v_max_f32_e32 v4, v4, v21
	v_max_f32_e64 v22, |v22|, |v22|
	v_max_f32_e32 v4, v4, v22
	v_max_f32_e64 v23, |v23|, |v23|
	v_max_f32_e32 v4, v4, v23
	v_max_f32_e64 v24, |v24|, |v24|
	v_max_f32_e32 v4, v4, v24
	v_max_f32_e64 v25, |v25|, |v25|
	v_max_f32_e32 v4, v4, v25
	v_max_f32_e64 v26, |v26|, |v26|
	v_max_f32_e32 v4, v4, v26
	v_max_f32_e64 v27, |v27|, |v27|
	v_max_f32_e32 v4, v4, v27
	v_max_f32_e64 v28, |v28|, |v28|
	v_max_f32_e32 v4, v4, v28
	v_max_f32_e64 v29, |v29|, |v29|
	v_max_f32_e32 v4, v4, v29
	v_max_f32_e64 v30, |v30|, |v30|
	v_max_f32_e32 v4, v4, v30
	v_max_f32_e64 v31, |v31|, |v31|
	v_max_f32_e32 v4, v4, v31
	global_load_dword v16, v[12:13], off
	global_load_dword v17, v[12:13], off offset:256
	global_load_dword v18, v[12:13], off offset:512
	global_load_dword v19, v[12:13], off offset:768
	global_load_dword v20, v[12:13], off offset:1024
	global_load_dword v21, v[12:13], off offset:1280
	global_load_dword v22, v[12:13], off offset:1536
	global_load_dword v23, v[12:13], off offset:1792
	global_load_dword v24, v[12:13], off offset:2048
	global_load_dword v25, v[12:13], off offset:2304
	global_load_dword v26, v[12:13], off offset:2560
	global_load_dword v27, v[12:13], off offset:2816
	global_load_dword v28, v[12:13], off offset:3072
	global_load_dword v29, v[12:13], off offset:3328
	global_load_dword v30, v[12:13], off offset:3584
	global_load_dword v31, v[12:13], off offset:3840
	v_lshl_add_u64 v[12:13], v[12:13], 0, s[98:99]
	s_waitcnt vmcnt(0)
	v_max_f32_e64 v16, |v16|, |v16|
	v_max_f32_e32 v4, v4, v16
	v_max_f32_e64 v17, |v17|, |v17|
	v_max_f32_e32 v4, v4, v17
	v_max_f32_e64 v18, |v18|, |v18|
	v_max_f32_e32 v4, v4, v18
	v_max_f32_e64 v19, |v19|, |v19|
	v_max_f32_e32 v4, v4, v19
	v_max_f32_e64 v20, |v20|, |v20|
	v_max_f32_e32 v4, v4, v20
	v_max_f32_e64 v21, |v21|, |v21|
	v_max_f32_e32 v4, v4, v21
	v_max_f32_e64 v22, |v22|, |v22|
	v_max_f32_e32 v4, v4, v22
	v_max_f32_e64 v23, |v23|, |v23|
	v_max_f32_e32 v4, v4, v23
	v_max_f32_e64 v24, |v24|, |v24|
	v_max_f32_e32 v4, v4, v24
	v_max_f32_e64 v25, |v25|, |v25|
	v_max_f32_e32 v4, v4, v25
	v_max_f32_e64 v26, |v26|, |v26|
	v_max_f32_e32 v4, v4, v26
	v_max_f32_e64 v27, |v27|, |v27|
	v_max_f32_e32 v4, v4, v27
	v_max_f32_e64 v28, |v28|, |v28|
	v_max_f32_e32 v4, v4, v28
	v_max_f32_e64 v29, |v29|, |v29|
	v_max_f32_e32 v4, v4, v29
	v_max_f32_e64 v30, |v30|, |v30|
	v_max_f32_e32 v4, v4, v30
	v_max_f32_e64 v31, |v31|, |v31|
	v_max_f32_e32 v4, v4, v31
	global_load_dword v16, v[12:13], off
	global_load_dword v17, v[12:13], off offset:256
	global_load_dword v18, v[12:13], off offset:512
	global_load_dword v19, v[12:13], off offset:768
	global_load_dword v20, v[12:13], off offset:1024
	global_load_dword v21, v[12:13], off offset:1280
	global_load_dword v22, v[12:13], off offset:1536
	global_load_dword v23, v[12:13], off offset:1792
	global_load_dword v24, v[12:13], off offset:2048
	global_load_dword v25, v[12:13], off offset:2304
	global_load_dword v26, v[12:13], off offset:2560
	global_load_dword v27, v[12:13], off offset:2816
	global_load_dword v28, v[12:13], off offset:3072
	global_load_dword v29, v[12:13], off offset:3328
	global_load_dword v30, v[12:13], off offset:3584
	global_load_dword v31, v[12:13], off offset:3840
	v_lshl_add_u64 v[12:13], v[12:13], 0, s[98:99]
	s_waitcnt vmcnt(0)
	v_max_f32_e64 v16, |v16|, |v16|
	v_max_f32_e32 v4, v4, v16
	v_max_f32_e64 v17, |v17|, |v17|
	v_max_f32_e32 v4, v4, v17
	v_max_f32_e64 v18, |v18|, |v18|
	v_max_f32_e32 v4, v4, v18
	v_max_f32_e64 v19, |v19|, |v19|
	v_max_f32_e32 v4, v4, v19
	v_max_f32_e64 v20, |v20|, |v20|
	v_max_f32_e32 v4, v4, v20
	v_max_f32_e64 v21, |v21|, |v21|
	v_max_f32_e32 v4, v4, v21
	v_max_f32_e64 v22, |v22|, |v22|
	v_max_f32_e32 v4, v4, v22
	v_max_f32_e64 v23, |v23|, |v23|
	v_max_f32_e32 v4, v4, v23
	v_max_f32_e64 v24, |v24|, |v24|
	v_max_f32_e32 v4, v4, v24
	v_max_f32_e64 v25, |v25|, |v25|
	v_max_f32_e32 v4, v4, v25
	v_max_f32_e64 v26, |v26|, |v26|
	v_max_f32_e32 v4, v4, v26
	v_max_f32_e64 v27, |v27|, |v27|
	v_max_f32_e32 v4, v4, v27
	v_max_f32_e64 v28, |v28|, |v28|
	v_max_f32_e32 v4, v4, v28
	v_max_f32_e64 v29, |v29|, |v29|
	v_max_f32_e32 v4, v4, v29
	v_max_f32_e64 v30, |v30|, |v30|
	v_max_f32_e32 v4, v4, v30
	v_max_f32_e64 v31, |v31|, |v31|
	v_max_f32_e32 v4, v4, v31
	global_load_dword v16, v[12:13], off
	global_load_dword v17, v[12:13], off offset:256
	global_load_dword v18, v[12:13], off offset:512
	global_load_dword v19, v[12:13], off offset:768
	global_load_dword v20, v[12:13], off offset:1024
	global_load_dword v21, v[12:13], off offset:1280
	global_load_dword v22, v[12:13], off offset:1536
	global_load_dword v23, v[12:13], off offset:1792
	global_load_dword v24, v[12:13], off offset:2048
	global_load_dword v25, v[12:13], off offset:2304
	v_mov_b32_e32 v26, 0
	v_cmp_gt_u32_e32 vcc, 8, v2
	s_and_saveexec_b64 s[6:7], vcc
	global_load_dword v26, v[12:13], off offset:2560
	s_or_b64 exec, exec, s[6:7]
	s_waitcnt vmcnt(0)
	v_max_f32_e64 v16, |v16|, |v16|
	v_max_f32_e32 v4, v4, v16
	v_max_f32_e64 v17, |v17|, |v17|
	v_max_f32_e32 v4, v4, v17
	v_max_f32_e64 v18, |v18|, |v18|
	v_max_f32_e32 v4, v4, v18
	v_max_f32_e64 v19, |v19|, |v19|
	v_max_f32_e32 v4, v4, v19
	v_max_f32_e64 v20, |v20|, |v20|
	v_max_f32_e32 v4, v4, v20
	v_max_f32_e64 v21, |v21|, |v21|
	v_max_f32_e32 v4, v4, v21
	v_max_f32_e64 v22, |v22|, |v22|
	v_max_f32_e32 v4, v4, v22
	v_max_f32_e64 v23, |v23|, |v23|
	v_max_f32_e32 v4, v4, v23
	v_max_f32_e64 v24, |v24|, |v24|
	v_max_f32_e32 v4, v4, v24
	v_max_f32_e64 v25, |v25|, |v25|
	v_max_f32_e32 v4, v4, v25
	v_max_f32_e64 v26, |v26|, |v26|
	v_max_f32_e32 v4, v4, v26
